# P11 final-output f32 stores marked nt (streamed, never re-read)
# baseline (speedup 1.0000x reference)
.LBB0_170:
	s_waitcnt vmcnt(7)
	v_fmamk_f32 v142, v242, 0x3a800000, v194
	v_cmp_gt_f32_e32 vcc, s19, v142
	v_mul_f32_e32 v143, 0x4b800000, v142
	s_nop 0
	v_cndmask_b32_e32 v142, v142, v143, vcc
	v_rsq_f32_e32 v142, v142
	s_nop 0
	v_mul_f32_e32 v143, 0x45800000, v142
	v_cndmask_b32_e32 v165, v142, v143, vcc
	v_lshlrev_b64 v[142:143], 11, v[146:147]
	v_lshl_add_u64 v[150:151], s[38:39], 0, v[142:143]
	v_lshl_add_u64 v[160:161], s[92:93], 0, v[142:143]
	v_lshlrev_b64 v[142:143], 1, v[144:145]
	v_lshl_add_u64 v[150:151], v[150:151], 0, v[142:143]
	v_lshl_add_u64 v[160:161], v[160:161], 0, v[142:143]
	global_load_dwordx4 v[166:169], v[150:151], off
	global_load_dwordx4 v[170:173], v[160:161], off
	v_mul_f32_e32 v126, v126, v165
	v_mul_f32_e32 v127, v127, v165
	v_mul_f32_e32 v126, 0xbfb8aa3b, v126
	v_mul_f32_e32 v122, v122, v165
	v_mul_f32_e32 v127, 0xbfb8aa3b, v127
	v_mul_f32_e32 v123, v123, v165
	v_exp_f32_e32 v126, v126
	v_mul_f32_e32 v122, 0xbfb8aa3b, v122
	v_exp_f32_e32 v127, v127
	v_mul_f32_e32 v123, 0xbfb8aa3b, v123
	v_mul_f32_e32 v128, v128, v165
	v_mul_f32_e32 v129, v129, v165
	v_exp_f32_e32 v122, v122
	v_exp_f32_e32 v123, v123
	v_mul_f32_e32 v128, 0xbfb8aa3b, v128
	v_mul_f32_e32 v124, v124, v165
	v_mul_f32_e32 v129, 0xbfb8aa3b, v129
	v_mul_f32_e32 v125, v125, v165
	v_exp_f32_e32 v128, v128
	v_mul_f32_e32 v124, 0xbfb8aa3b, v124
	v_exp_f32_e32 v129, v129
	v_mul_f32_e32 v125, 0xbfb8aa3b, v125
	v_exp_f32_e32 v124, v124
	v_exp_f32_e32 v125, v125
	v_add_f32_e32 v126, 1.0, v126
	v_add_f32_e32 v127, 1.0, v127
	v_rcp_f32_e32 v126, v126
	v_add_f32_e32 v122, 1.0, v122
	v_rcp_f32_e32 v127, v127
	v_add_f32_e32 v123, 1.0, v123
	v_rcp_f32_e32 v122, v122
	v_rcp_f32_e32 v123, v123
	v_add_f32_e32 v128, 1.0, v128
	v_add_f32_e32 v129, 1.0, v129
	v_rcp_f32_e32 v128, v128
	v_add_f32_e32 v124, 1.0, v124
	v_rcp_f32_e32 v129, v129
	v_add_f32_e32 v125, 1.0, v125
	v_rcp_f32_e32 v124, v124
	v_rcp_f32_e32 v125, v125
	v_lshlrev_b64 v[144:145], 2, v[144:145]
	v_mul_f32_e32 v118, v118, v165
	v_mul_f32_e32 v119, v119, v165
	v_mul_f32_e32 v120, v120, v165
	v_mul_f32_e32 v121, v121, v165
	v_mul_f32_e32 v118, 0xbfb8aa3b, v118
	v_mul_f32_e32 v114, v114, v165
	v_mul_f32_e32 v119, 0xbfb8aa3b, v119
	v_mul_f32_e32 v115, v115, v165
	v_mul_f32_e32 v120, 0xbfb8aa3b, v120
	v_mul_f32_e32 v116, v116, v165
	v_mul_f32_e32 v121, 0xbfb8aa3b, v121
	v_mul_f32_e32 v117, v117, v165
	v_exp_f32_e32 v118, v118
	v_mul_f32_e32 v114, 0xbfb8aa3b, v114
	v_exp_f32_e32 v119, v119
	v_mul_f32_e32 v115, 0xbfb8aa3b, v115
	v_exp_f32_e32 v120, v120
	v_mul_f32_e32 v116, 0xbfb8aa3b, v116
	v_exp_f32_e32 v121, v121
	v_mul_f32_e32 v117, 0xbfb8aa3b, v117
	v_exp_f32_e32 v114, v114
	v_exp_f32_e32 v115, v115
	v_exp_f32_e32 v116, v116
	v_exp_f32_e32 v117, v117
	v_add_f32_e32 v118, 1.0, v118
	v_add_f32_e32 v119, 1.0, v119
	v_add_f32_e32 v120, 1.0, v120
	v_add_f32_e32 v121, 1.0, v121
	v_rcp_f32_e32 v118, v118
	v_add_f32_e32 v114, 1.0, v114
	v_rcp_f32_e32 v119, v119
	v_add_f32_e32 v115, 1.0, v115
	v_rcp_f32_e32 v120, v120
	v_add_f32_e32 v116, 1.0, v116
	v_rcp_f32_e32 v121, v121
	v_add_f32_e32 v117, 1.0, v117
	v_rcp_f32_e32 v114, v114
	s_waitcnt vmcnt(1)
	v_lshlrev_b32_e32 v162, 16, v166
	v_and_b32_e32 v163, 0xffff0000, v166
	s_waitcnt vmcnt(0)
	v_lshlrev_b32_e32 v174, 16, v170
	v_and_b32_e32 v175, 0xffff0000, v170
	v_pk_fma_f32 v[126:127], v[126:127], v[174:175], v[162:163]
	v_lshlrev_b32_e32 v162, 16, v168
	v_and_b32_e32 v163, 0xffff0000, v168
	v_lshlrev_b32_e32 v174, 16, v172
	v_and_b32_e32 v175, 0xffff0000, v172
	v_pk_fma_f32 v[122:123], v[122:123], v[174:175], v[162:163]
	v_lshlrev_b32_e32 v162, 16, v167
	v_and_b32_e32 v163, 0xffff0000, v167
	v_lshlrev_b32_e32 v166, 16, v171
	v_and_b32_e32 v167, 0xffff0000, v171
	v_pk_fma_f32 v[128:129], v[128:129], v[166:167], v[162:163]
	v_lshlrev_b32_e32 v162, 16, v169
	v_and_b32_e32 v163, 0xffff0000, v169
	v_lshlrev_b32_e32 v166, 16, v173
	v_and_b32_e32 v167, 0xffff0000, v173
	v_pk_fma_f32 v[124:125], v[124:125], v[166:167], v[162:163]
	v_lshlrev_b64 v[162:163], 12, v[146:147]
	v_lshl_add_u64 v[162:163], s[88:89], 0, v[162:163]
	v_lshl_add_u64 v[162:163], v[162:163], 0, v[144:145]
	global_store_dwordx4 v[162:163], v[126:129], off nt
	global_store_dwordx4 v[162:163], v[122:125], off offset:16 nt
	global_load_dwordx4 v[122:125], v[150:151], off offset:256
	s_nop 0
	global_load_dwordx4 v[126:129], v[160:161], off offset:256
	v_rcp_f32_e32 v115, v115
	v_rcp_f32_e32 v116, v116
	v_rcp_f32_e32 v117, v117
	s_waitcnt vmcnt(1)
	v_lshlrev_b32_e32 v150, 16, v122
	v_and_b32_e32 v151, 0xffff0000, v122
	s_waitcnt vmcnt(0)
	v_lshlrev_b32_e32 v160, 16, v126
	v_and_b32_e32 v161, 0xffff0000, v126
	v_lshlrev_b32_e32 v122, 16, v123
	v_and_b32_e32 v123, 0xffff0000, v123
	v_lshlrev_b32_e32 v126, 16, v127
	v_and_b32_e32 v127, 0xffff0000, v127
	v_pk_fma_f32 v[118:119], v[118:119], v[160:161], v[150:151]
	v_lshlrev_b32_e32 v150, 16, v124
	v_and_b32_e32 v151, 0xffff0000, v124
	v_lshlrev_b32_e32 v160, 16, v128
	v_and_b32_e32 v161, 0xffff0000, v128
	v_pk_fma_f32 v[120:121], v[120:121], v[126:127], v[122:123]
	v_lshlrev_b32_e32 v122, 16, v125
	v_and_b32_e32 v123, 0xffff0000, v125
	v_lshlrev_b32_e32 v124, 16, v129
	v_and_b32_e32 v125, 0xffff0000, v129
	v_pk_fma_f32 v[114:115], v[114:115], v[160:161], v[150:151]
	v_pk_fma_f32 v[116:117], v[116:117], v[124:125], v[122:123]
	global_store_dwordx4 v[162:163], v[118:121], off offset:512 nt
	global_store_dwordx4 v[162:163], v[114:117], off offset:528 nt
	s_nop 0
	s_nop 0
	v_or_b32_e32 v116, 16, v146
	v_ashrrev_i32_e32 v117, 31, v116
	s_waitcnt vmcnt(14)
	v_fmamk_f32 v114, v243, 0x3a800000, v194
	v_cmp_gt_f32_e32 vcc, s19, v114
	v_mul_f32_e32 v115, 0x4b800000, v114
	s_nop 0
	v_cndmask_b32_e32 v114, v114, v115, vcc
	v_rsq_f32_e32 v114, v114
	s_nop 0
	v_mul_f32_e32 v115, 0x45800000, v114
	v_cndmask_b32_e32 v120, v114, v115, vcc
	v_lshlrev_b64 v[114:115], 11, v[116:117]
	v_lshl_add_u64 v[122:123], s[38:39], 0, v[114:115]
	v_lshl_add_u64 v[118:119], s[92:93], 0, v[114:115]
	v_lshl_add_u64 v[114:115], v[122:123], 0, v[142:143]
	v_lshl_add_u64 v[118:119], v[118:119], 0, v[142:143]
	global_load_dwordx4 v[122:125], v[114:115], off
	global_load_dwordx4 v[126:129], v[118:119], off
	v_mul_f32_e32 v110, v110, v120
	v_mul_f32_e32 v111, v111, v120
	v_mul_f32_e32 v112, v112, v120
	v_mul_f32_e32 v113, v113, v120
	v_mul_f32_e32 v110, 0xbfb8aa3b, v110
	v_mul_f32_e32 v106, v106, v120
	v_mul_f32_e32 v111, 0xbfb8aa3b, v111
	v_mul_f32_e32 v107, v107, v120
	v_mul_f32_e32 v112, 0xbfb8aa3b, v112
	v_mul_f32_e32 v108, v108, v120
	v_mul_f32_e32 v113, 0xbfb8aa3b, v113
	v_mul_f32_e32 v109, v109, v120
	v_exp_f32_e32 v110, v110
	v_mul_f32_e32 v106, 0xbfb8aa3b, v106
	v_exp_f32_e32 v111, v111
	v_mul_f32_e32 v107, 0xbfb8aa3b, v107
	v_exp_f32_e32 v112, v112
	v_mul_f32_e32 v108, 0xbfb8aa3b, v108
	v_exp_f32_e32 v113, v113
	v_mul_f32_e32 v109, 0xbfb8aa3b, v109
	v_exp_f32_e32 v106, v106
	v_exp_f32_e32 v107, v107
	v_exp_f32_e32 v108, v108
	v_exp_f32_e32 v109, v109
	v_add_f32_e32 v110, 1.0, v110
	v_add_f32_e32 v111, 1.0, v111
	v_add_f32_e32 v112, 1.0, v112
	v_add_f32_e32 v113, 1.0, v113
	v_rcp_f32_e32 v110, v110
	v_add_f32_e32 v106, 1.0, v106
	v_rcp_f32_e32 v111, v111
	v_add_f32_e32 v107, 1.0, v107
	v_rcp_f32_e32 v112, v112
	v_add_f32_e32 v108, 1.0, v108
	v_rcp_f32_e32 v113, v113
	v_add_f32_e32 v109, 1.0, v109
	v_rcp_f32_e32 v106, v106
	v_rcp_f32_e32 v107, v107
	v_rcp_f32_e32 v108, v108
	v_rcp_f32_e32 v109, v109
	v_lshlrev_b64 v[116:117], 12, v[116:117]
	v_lshl_add_u64 v[116:117], s[88:89], 0, v[116:117]
	v_lshl_add_u64 v[116:117], v[116:117], 0, v[144:145]
	v_mul_f32_e32 v102, v102, v120
	v_mul_f32_e32 v103, v103, v120
	v_mul_f32_e32 v104, v104, v120
	v_mul_f32_e32 v105, v105, v120
	v_mul_f32_e32 v102, 0xbfb8aa3b, v102
	v_mul_f32_e32 v98, v98, v120
	v_mul_f32_e32 v103, 0xbfb8aa3b, v103
	v_mul_f32_e32 v99, v99, v120
	v_mul_f32_e32 v104, 0xbfb8aa3b, v104
	v_mul_f32_e32 v100, v100, v120
	v_mul_f32_e32 v105, 0xbfb8aa3b, v105
	v_mul_f32_e32 v101, v101, v120
	v_exp_f32_e32 v102, v102
	v_mul_f32_e32 v98, 0xbfb8aa3b, v98
	v_exp_f32_e32 v103, v103
	v_mul_f32_e32 v99, 0xbfb8aa3b, v99
	v_exp_f32_e32 v104, v104
	v_mul_f32_e32 v100, 0xbfb8aa3b, v100
	v_exp_f32_e32 v105, v105
	v_mul_f32_e32 v101, 0xbfb8aa3b, v101
	v_exp_f32_e32 v98, v98
	v_exp_f32_e32 v99, v99
	v_exp_f32_e32 v100, v100
	v_exp_f32_e32 v101, v101
	v_add_f32_e32 v102, 1.0, v102
	v_add_f32_e32 v103, 1.0, v103
	v_add_f32_e32 v104, 1.0, v104
	v_add_f32_e32 v105, 1.0, v105
	v_rcp_f32_e32 v102, v102
	v_add_f32_e32 v98, 1.0, v98
	v_rcp_f32_e32 v103, v103
	v_add_f32_e32 v99, 1.0, v99
	v_rcp_f32_e32 v104, v104
	v_add_f32_e32 v100, 1.0, v100
	v_rcp_f32_e32 v105, v105
	s_waitcnt vmcnt(1)
	v_lshlrev_b32_e32 v150, 16, v122
	v_and_b32_e32 v151, 0xffff0000, v122
	s_waitcnt vmcnt(0)
	v_lshlrev_b32_e32 v160, 16, v126
	v_and_b32_e32 v161, 0xffff0000, v126
	v_lshlrev_b32_e32 v122, 16, v123
	v_and_b32_e32 v123, 0xffff0000, v123
	v_lshlrev_b32_e32 v126, 16, v127
	v_and_b32_e32 v127, 0xffff0000, v127
	v_pk_fma_f32 v[110:111], v[110:111], v[160:161], v[150:151]
	v_lshlrev_b32_e32 v150, 16, v124
	v_and_b32_e32 v151, 0xffff0000, v124
	v_lshlrev_b32_e32 v160, 16, v128
	v_and_b32_e32 v161, 0xffff0000, v128
	v_pk_fma_f32 v[112:113], v[112:113], v[126:127], v[122:123]
	v_lshlrev_b32_e32 v122, 16, v125
	v_and_b32_e32 v123, 0xffff0000, v125
	v_lshlrev_b32_e32 v124, 16, v129
	v_and_b32_e32 v125, 0xffff0000, v129
	v_pk_fma_f32 v[106:107], v[106:107], v[160:161], v[150:151]
	v_pk_fma_f32 v[108:109], v[108:109], v[124:125], v[122:123]
	global_store_dwordx4 v[116:117], v[110:113], off nt
	global_store_dwordx4 v[116:117], v[106:109], off offset:16 nt
	global_load_dwordx4 v[106:109], v[114:115], off offset:256
	s_nop 0
	global_load_dwordx4 v[110:113], v[118:119], off offset:256
	v_add_f32_e32 v101, 1.0, v101
	v_rcp_f32_e32 v98, v98
	v_rcp_f32_e32 v99, v99
	v_rcp_f32_e32 v100, v100
	v_rcp_f32_e32 v101, v101
	s_waitcnt vmcnt(1)
	v_lshlrev_b32_e32 v114, 16, v106
	v_and_b32_e32 v115, 0xffff0000, v106
	s_waitcnt vmcnt(0)
	v_lshlrev_b32_e32 v118, 16, v110
	v_and_b32_e32 v119, 0xffff0000, v110
	v_lshlrev_b32_e32 v106, 16, v107
	v_and_b32_e32 v107, 0xffff0000, v107
	v_lshlrev_b32_e32 v110, 16, v111
	v_and_b32_e32 v111, 0xffff0000, v111
	v_pk_fma_f32 v[102:103], v[102:103], v[118:119], v[114:115]
	v_lshlrev_b32_e32 v114, 16, v108
	v_and_b32_e32 v115, 0xffff0000, v108
	v_lshlrev_b32_e32 v118, 16, v112
	v_and_b32_e32 v119, 0xffff0000, v112
	v_pk_fma_f32 v[104:105], v[104:105], v[110:111], v[106:107]
	v_lshlrev_b32_e32 v106, 16, v109
	v_and_b32_e32 v107, 0xffff0000, v109
	v_lshlrev_b32_e32 v108, 16, v113
	v_and_b32_e32 v109, 0xffff0000, v113
	v_pk_fma_f32 v[98:99], v[98:99], v[118:119], v[114:115]
	v_pk_fma_f32 v[100:101], v[100:101], v[108:109], v[106:107]
	global_store_dwordx4 v[116:117], v[102:105], off offset:512 nt
	global_store_dwordx4 v[116:117], v[98:101], off offset:528 nt
	s_nop 0
	s_nop 0
	v_or_b32_e32 v100, 32, v146
	v_ashrrev_i32_e32 v101, 31, v100
	s_waitcnt vmcnt(21)
	v_fmamk_f32 v98, v244, 0x3a800000, v194
	v_cmp_gt_f32_e32 vcc, s19, v98
	v_mul_f32_e32 v99, 0x4b800000, v98
	s_nop 0
	v_cndmask_b32_e32 v98, v98, v99, vcc
	v_rsq_f32_e32 v98, v98
	s_nop 0
	v_mul_f32_e32 v99, 0x45800000, v98
	v_cndmask_b32_e32 v104, v98, v99, vcc
	v_lshlrev_b64 v[98:99], 11, v[100:101]
	v_lshl_add_u64 v[106:107], s[38:39], 0, v[98:99]
	v_lshl_add_u64 v[102:103], s[92:93], 0, v[98:99]
	v_lshl_add_u64 v[98:99], v[106:107], 0, v[142:143]
	v_lshl_add_u64 v[102:103], v[102:103], 0, v[142:143]
	global_load_dwordx4 v[106:109], v[98:99], off
	global_load_dwordx4 v[110:113], v[102:103], off
	v_mul_f32_e32 v94, v94, v104
	v_mul_f32_e32 v95, v95, v104
	v_mul_f32_e32 v96, v96, v104
	v_mul_f32_e32 v97, v97, v104
	v_mul_f32_e32 v94, 0xbfb8aa3b, v94
	v_mul_f32_e32 v90, v90, v104
	v_mul_f32_e32 v95, 0xbfb8aa3b, v95
	v_mul_f32_e32 v91, v91, v104
	v_mul_f32_e32 v96, 0xbfb8aa3b, v96
	v_mul_f32_e32 v92, v92, v104
	v_mul_f32_e32 v97, 0xbfb8aa3b, v97
	v_mul_f32_e32 v93, v93, v104
	v_exp_f32_e32 v94, v94
	v_mul_f32_e32 v90, 0xbfb8aa3b, v90
	v_exp_f32_e32 v95, v95
	v_mul_f32_e32 v91, 0xbfb8aa3b, v91
	v_exp_f32_e32 v96, v96
	v_mul_f32_e32 v92, 0xbfb8aa3b, v92
	v_exp_f32_e32 v97, v97
	v_mul_f32_e32 v93, 0xbfb8aa3b, v93
	v_exp_f32_e32 v90, v90
	v_exp_f32_e32 v91, v91
	v_exp_f32_e32 v92, v92
	v_exp_f32_e32 v93, v93
	v_add_f32_e32 v94, 1.0, v94
	v_add_f32_e32 v95, 1.0, v95
	v_add_f32_e32 v96, 1.0, v96
	v_add_f32_e32 v97, 1.0, v97
	v_rcp_f32_e32 v94, v94
	v_add_f32_e32 v90, 1.0, v90
	v_rcp_f32_e32 v95, v95
	v_add_f32_e32 v91, 1.0, v91
	v_rcp_f32_e32 v96, v96
	v_add_f32_e32 v92, 1.0, v92
	v_rcp_f32_e32 v97, v97
	v_add_f32_e32 v93, 1.0, v93
	v_rcp_f32_e32 v90, v90
	v_rcp_f32_e32 v91, v91
	v_rcp_f32_e32 v92, v92
	v_rcp_f32_e32 v93, v93
	v_lshlrev_b64 v[100:101], 12, v[100:101]
	v_lshl_add_u64 v[100:101], s[88:89], 0, v[100:101]
	v_lshl_add_u64 v[100:101], v[100:101], 0, v[144:145]
	v_mul_f32_e32 v86, v86, v104
	v_mul_f32_e32 v87, v87, v104
	v_mul_f32_e32 v88, v88, v104
	v_mul_f32_e32 v89, v89, v104
	v_mul_f32_e32 v86, 0xbfb8aa3b, v86
	v_mul_f32_e32 v82, v82, v104
	v_mul_f32_e32 v87, 0xbfb8aa3b, v87
	v_mul_f32_e32 v83, v83, v104
	v_mul_f32_e32 v88, 0xbfb8aa3b, v88
	v_mul_f32_e32 v84, v84, v104
	v_mul_f32_e32 v89, 0xbfb8aa3b, v89
	v_mul_f32_e32 v85, v85, v104
	v_exp_f32_e32 v86, v86
	v_mul_f32_e32 v82, 0xbfb8aa3b, v82
	v_exp_f32_e32 v87, v87
	v_mul_f32_e32 v83, 0xbfb8aa3b, v83
	v_exp_f32_e32 v88, v88
	v_mul_f32_e32 v84, 0xbfb8aa3b, v84
	v_exp_f32_e32 v89, v89
	v_mul_f32_e32 v85, 0xbfb8aa3b, v85
	v_exp_f32_e32 v82, v82
	v_exp_f32_e32 v83, v83
	v_exp_f32_e32 v84, v84
	v_exp_f32_e32 v85, v85
	v_add_f32_e32 v86, 1.0, v86
	v_add_f32_e32 v87, 1.0, v87
	v_add_f32_e32 v88, 1.0, v88
	v_add_f32_e32 v89, 1.0, v89
	v_rcp_f32_e32 v86, v86
	v_add_f32_e32 v82, 1.0, v82
	v_rcp_f32_e32 v87, v87
	v_add_f32_e32 v83, 1.0, v83
	v_rcp_f32_e32 v88, v88
	v_add_f32_e32 v84, 1.0, v84
	v_rcp_f32_e32 v89, v89
	s_waitcnt vmcnt(1)
	v_lshlrev_b32_e32 v114, 16, v106
	v_and_b32_e32 v115, 0xffff0000, v106
	s_waitcnt vmcnt(0)
	v_lshlrev_b32_e32 v116, 16, v110
	v_and_b32_e32 v117, 0xffff0000, v110
	v_lshlrev_b32_e32 v106, 16, v107
	v_and_b32_e32 v107, 0xffff0000, v107
	v_lshlrev_b32_e32 v110, 16, v111
	v_and_b32_e32 v111, 0xffff0000, v111
	v_pk_fma_f32 v[94:95], v[94:95], v[116:117], v[114:115]
	v_lshlrev_b32_e32 v114, 16, v108
	v_and_b32_e32 v115, 0xffff0000, v108
	v_lshlrev_b32_e32 v116, 16, v112
	v_and_b32_e32 v117, 0xffff0000, v112
	v_pk_fma_f32 v[96:97], v[96:97], v[110:111], v[106:107]
	v_lshlrev_b32_e32 v106, 16, v109
	v_and_b32_e32 v107, 0xffff0000, v109
	v_lshlrev_b32_e32 v108, 16, v113
	v_and_b32_e32 v109, 0xffff0000, v113
	v_pk_fma_f32 v[90:91], v[90:91], v[116:117], v[114:115]
	v_pk_fma_f32 v[92:93], v[92:93], v[108:109], v[106:107]
	global_store_dwordx4 v[100:101], v[94:97], off nt
	global_store_dwordx4 v[100:101], v[90:93], off offset:16 nt
	global_load_dwordx4 v[90:93], v[98:99], off offset:256
	s_nop 0
	global_load_dwordx4 v[94:97], v[102:103], off offset:256
	v_add_f32_e32 v85, 1.0, v85
	v_rcp_f32_e32 v82, v82
	v_rcp_f32_e32 v83, v83
	v_rcp_f32_e32 v84, v84
	v_rcp_f32_e32 v85, v85
	s_waitcnt vmcnt(1)
	v_lshlrev_b32_e32 v98, 16, v90
	v_and_b32_e32 v99, 0xffff0000, v90
	s_waitcnt vmcnt(0)
	v_lshlrev_b32_e32 v102, 16, v94
	v_and_b32_e32 v103, 0xffff0000, v94
	v_lshlrev_b32_e32 v90, 16, v91
	v_and_b32_e32 v91, 0xffff0000, v91
	v_lshlrev_b32_e32 v94, 16, v95
	v_and_b32_e32 v95, 0xffff0000, v95
	v_pk_fma_f32 v[86:87], v[86:87], v[102:103], v[98:99]
	v_lshlrev_b32_e32 v98, 16, v92
	v_and_b32_e32 v99, 0xffff0000, v92
	v_lshlrev_b32_e32 v102, 16, v96
	v_and_b32_e32 v103, 0xffff0000, v96
	v_pk_fma_f32 v[88:89], v[88:89], v[94:95], v[90:91]
	v_lshlrev_b32_e32 v90, 16, v93
	v_and_b32_e32 v91, 0xffff0000, v93
	v_lshlrev_b32_e32 v92, 16, v97
	v_and_b32_e32 v93, 0xffff0000, v97
	v_pk_fma_f32 v[82:83], v[82:83], v[102:103], v[98:99]
	v_pk_fma_f32 v[84:85], v[84:85], v[92:93], v[90:91]
	global_store_dwordx4 v[100:101], v[86:89], off offset:512 nt
	global_store_dwordx4 v[100:101], v[82:85], off offset:528 nt
	s_nop 0
	s_nop 0
	v_or_b32_e32 v84, 48, v146
	v_ashrrev_i32_e32 v85, 31, v84
	s_waitcnt vmcnt(28)
	v_fmamk_f32 v82, v245, 0x3a800000, v194
	v_cmp_gt_f32_e32 vcc, s19, v82
	v_mul_f32_e32 v83, 0x4b800000, v82
	s_nop 0
	v_cndmask_b32_e32 v82, v82, v83, vcc
	v_rsq_f32_e32 v82, v82
	s_nop 0
	v_mul_f32_e32 v83, 0x45800000, v82
	v_cndmask_b32_e32 v88, v82, v83, vcc
	v_lshlrev_b64 v[82:83], 11, v[84:85]
	v_lshl_add_u64 v[90:91], s[38:39], 0, v[82:83]
	v_lshl_add_u64 v[86:87], s[92:93], 0, v[82:83]
	v_lshl_add_u64 v[82:83], v[90:91], 0, v[142:143]
	v_lshl_add_u64 v[86:87], v[86:87], 0, v[142:143]
	global_load_dwordx4 v[90:93], v[82:83], off
	global_load_dwordx4 v[94:97], v[86:87], off
	v_mul_f32_e32 v76, v76, v88
	v_mul_f32_e32 v77, v77, v88
	v_mul_f32_e32 v78, v78, v88
	v_mul_f32_e32 v79, v79, v88
	v_mul_f32_e32 v76, 0xbfb8aa3b, v76
	v_mul_f32_e32 v72, v72, v88
	v_mul_f32_e32 v77, 0xbfb8aa3b, v77
	v_mul_f32_e32 v73, v73, v88
	v_mul_f32_e32 v78, 0xbfb8aa3b, v78
	v_mul_f32_e32 v74, v74, v88
	v_mul_f32_e32 v79, 0xbfb8aa3b, v79
	v_mul_f32_e32 v75, v75, v88
	v_exp_f32_e32 v76, v76
	v_mul_f32_e32 v72, 0xbfb8aa3b, v72
	v_exp_f32_e32 v77, v77
	v_mul_f32_e32 v73, 0xbfb8aa3b, v73
	v_exp_f32_e32 v78, v78
	v_mul_f32_e32 v74, 0xbfb8aa3b, v74
	v_exp_f32_e32 v79, v79
	v_mul_f32_e32 v75, 0xbfb8aa3b, v75
	v_exp_f32_e32 v72, v72
	v_exp_f32_e32 v73, v73
	v_exp_f32_e32 v74, v74
	v_exp_f32_e32 v75, v75
	v_add_f32_e32 v76, 1.0, v76
	v_add_f32_e32 v77, 1.0, v77
	v_add_f32_e32 v78, 1.0, v78
	v_add_f32_e32 v79, 1.0, v79
	v_rcp_f32_e32 v76, v76
	v_add_f32_e32 v72, 1.0, v72
	v_rcp_f32_e32 v77, v77
	v_add_f32_e32 v73, 1.0, v73
	v_rcp_f32_e32 v78, v78
	v_add_f32_e32 v74, 1.0, v74
	v_rcp_f32_e32 v79, v79
	v_add_f32_e32 v75, 1.0, v75
	v_rcp_f32_e32 v72, v72
	v_rcp_f32_e32 v73, v73
	v_rcp_f32_e32 v74, v74
	v_rcp_f32_e32 v75, v75
	v_lshlrev_b64 v[84:85], 12, v[84:85]
	v_lshl_add_u64 v[84:85], s[88:89], 0, v[84:85]
	v_lshl_add_u64 v[84:85], v[84:85], 0, v[144:145]
	v_mul_f32_e32 v68, v68, v88
	v_mul_f32_e32 v69, v69, v88
	v_mul_f32_e32 v70, v70, v88
	v_mul_f32_e32 v71, v71, v88
	v_mul_f32_e32 v68, 0xbfb8aa3b, v68
	v_mul_f32_e32 v69, 0xbfb8aa3b, v69
	v_mul_f32_e32 v70, 0xbfb8aa3b, v70
	v_mul_f32_e32 v66, v66, v88
	v_mul_f32_e32 v71, 0xbfb8aa3b, v71
	v_mul_f32_e32 v67, v67, v88
	v_exp_f32_e32 v68, v68
	v_mul_f32_e32 v64, v64, v88
	v_exp_f32_e32 v69, v69
	v_mul_f32_e32 v65, v65, v88
	v_exp_f32_e32 v70, v70
	v_mul_f32_e32 v66, 0xbfb8aa3b, v66
	v_exp_f32_e32 v71, v71
	v_mul_f32_e32 v67, 0xbfb8aa3b, v67
	v_mul_f32_e32 v64, 0xbfb8aa3b, v64
	v_mul_f32_e32 v65, 0xbfb8aa3b, v65
	v_exp_f32_e32 v66, v66
	v_exp_f32_e32 v67, v67
	v_exp_f32_e32 v64, v64
	v_exp_f32_e32 v65, v65
	v_add_f32_e32 v68, 1.0, v68
	v_add_f32_e32 v69, 1.0, v69
	v_add_f32_e32 v70, 1.0, v70
	v_add_f32_e32 v71, 1.0, v71
	v_rcp_f32_e32 v68, v68
	v_rcp_f32_e32 v69, v69
	v_rcp_f32_e32 v70, v70
	v_add_f32_e32 v66, 1.0, v66
	v_rcp_f32_e32 v71, v71
	v_add_f32_e32 v67, 1.0, v67
	v_add_f32_e32 v64, 1.0, v64
	s_waitcnt vmcnt(1)
	v_lshlrev_b32_e32 v98, 16, v90
	v_and_b32_e32 v99, 0xffff0000, v90
	s_waitcnt vmcnt(0)
	v_lshlrev_b32_e32 v100, 16, v94
	v_and_b32_e32 v101, 0xffff0000, v94
	v_lshlrev_b32_e32 v90, 16, v91
	v_and_b32_e32 v91, 0xffff0000, v91
	v_lshlrev_b32_e32 v94, 16, v95
	v_and_b32_e32 v95, 0xffff0000, v95
	v_pk_fma_f32 v[76:77], v[76:77], v[100:101], v[98:99]
	v_lshlrev_b32_e32 v98, 16, v92
	v_and_b32_e32 v99, 0xffff0000, v92
	v_lshlrev_b32_e32 v100, 16, v96
	v_and_b32_e32 v101, 0xffff0000, v96
	v_pk_fma_f32 v[78:79], v[78:79], v[94:95], v[90:91]
	v_lshlrev_b32_e32 v90, 16, v93
	v_and_b32_e32 v91, 0xffff0000, v93
	v_lshlrev_b32_e32 v92, 16, v97
	v_and_b32_e32 v93, 0xffff0000, v97
	v_pk_fma_f32 v[72:73], v[72:73], v[100:101], v[98:99]
	v_pk_fma_f32 v[74:75], v[74:75], v[92:93], v[90:91]
	global_store_dwordx4 v[84:85], v[76:79], off nt
	global_store_dwordx4 v[84:85], v[72:75], off offset:16 nt
	global_load_dwordx4 v[72:75], v[82:83], off offset:256
	s_nop 0
	global_load_dwordx4 v[76:79], v[86:87], off offset:256
	v_add_f32_e32 v65, 1.0, v65
	v_rcp_f32_e32 v66, v66
	v_rcp_f32_e32 v67, v67
	v_rcp_f32_e32 v64, v64
	v_rcp_f32_e32 v65, v65
	s_waitcnt vmcnt(1)
	v_lshlrev_b32_e32 v82, 16, v72
	v_and_b32_e32 v83, 0xffff0000, v72
	s_waitcnt vmcnt(0)
	v_lshlrev_b32_e32 v86, 16, v76
	v_and_b32_e32 v87, 0xffff0000, v76
	v_lshlrev_b32_e32 v72, 16, v73
	v_and_b32_e32 v73, 0xffff0000, v73
	v_lshlrev_b32_e32 v76, 16, v77
	v_and_b32_e32 v77, 0xffff0000, v77
	v_pk_fma_f32 v[68:69], v[68:69], v[86:87], v[82:83]
	v_lshlrev_b32_e32 v82, 16, v74
	v_and_b32_e32 v83, 0xffff0000, v74
	v_pk_fma_f32 v[70:71], v[70:71], v[76:77], v[72:73]
	v_lshlrev_b32_e32 v72, 16, v75
	v_and_b32_e32 v73, 0xffff0000, v75
	v_lshlrev_b32_e32 v74, 16, v79
	v_and_b32_e32 v75, 0xffff0000, v79
	v_lshlrev_b32_e32 v86, 16, v78
	v_and_b32_e32 v87, 0xffff0000, v78
	v_pk_fma_f32 v[66:67], v[66:67], v[74:75], v[72:73]
	v_pk_fma_f32 v[64:65], v[64:65], v[86:87], v[82:83]
	global_store_dwordx4 v[84:85], v[68:71], off offset:512 nt
	global_store_dwordx4 v[84:85], v[64:67], off offset:528 nt
	s_nop 1
	v_add_u32_e32 v66, 0x80, v146
	v_ashrrev_i32_e32 v67, 31, v66
	v_lshl_add_u64 v[64:65], v[66:67], 2, s[90:91]
	v_add_co_u32_e32 v64, vcc, s11, v64
	s_nop 1
	v_addc_co_u32_e32 v65, vcc, 0, v65, vcc
	s_nop 0
	s_waitcnt vmcnt(35)
	v_fmamk_f32 v64, v246, 0x3a800000, v194
	v_cmp_gt_f32_e32 vcc, s19, v64
	v_mul_f32_e32 v65, 0x4b800000, v64
	s_nop 0
	v_cndmask_b32_e32 v64, v64, v65, vcc
	v_rsq_f32_e32 v64, v64
	s_nop 0
	v_mul_f32_e32 v65, 0x45800000, v64
	v_cndmask_b32_e32 v70, v64, v65, vcc
	v_lshlrev_b64 v[64:65], 11, v[66:67]
	v_lshl_add_u64 v[72:73], s[38:39], 0, v[64:65]
	v_lshl_add_u64 v[68:69], s[92:93], 0, v[64:65]
	v_lshl_add_u64 v[64:65], v[72:73], 0, v[142:143]
	v_lshl_add_u64 v[68:69], v[68:69], 0, v[142:143]
	global_load_dwordx4 v[72:75], v[64:65], off
	global_load_dwordx4 v[76:79], v[68:69], off
	v_mul_f32_e32 v60, v60, v70
	v_mul_f32_e32 v61, v61, v70
	v_mul_f32_e32 v62, v62, v70
	v_mul_f32_e32 v63, v63, v70
	v_mul_f32_e32 v60, 0xbfb8aa3b, v60
	v_mul_f32_e32 v56, v56, v70
	v_mul_f32_e32 v61, 0xbfb8aa3b, v61
	v_mul_f32_e32 v57, v57, v70
	v_mul_f32_e32 v62, 0xbfb8aa3b, v62
	v_mul_f32_e32 v58, v58, v70
	v_mul_f32_e32 v63, 0xbfb8aa3b, v63
	v_mul_f32_e32 v59, v59, v70
	v_exp_f32_e32 v60, v60
	v_mul_f32_e32 v56, 0xbfb8aa3b, v56
	v_exp_f32_e32 v61, v61
	v_mul_f32_e32 v57, 0xbfb8aa3b, v57
	v_exp_f32_e32 v62, v62
	v_mul_f32_e32 v58, 0xbfb8aa3b, v58
	v_exp_f32_e32 v63, v63
	v_mul_f32_e32 v59, 0xbfb8aa3b, v59
	v_exp_f32_e32 v56, v56
	v_exp_f32_e32 v57, v57
	v_exp_f32_e32 v58, v58
	v_exp_f32_e32 v59, v59
	v_add_f32_e32 v60, 1.0, v60
	v_add_f32_e32 v61, 1.0, v61
	v_add_f32_e32 v62, 1.0, v62
	v_add_f32_e32 v63, 1.0, v63
	v_rcp_f32_e32 v60, v60
	v_add_f32_e32 v56, 1.0, v56
	v_rcp_f32_e32 v61, v61
	v_add_f32_e32 v57, 1.0, v57
	v_rcp_f32_e32 v62, v62
	v_add_f32_e32 v58, 1.0, v58
	v_rcp_f32_e32 v63, v63
	v_add_f32_e32 v59, 1.0, v59
	v_rcp_f32_e32 v56, v56
	v_rcp_f32_e32 v57, v57
	v_rcp_f32_e32 v58, v58
	v_rcp_f32_e32 v59, v59
	v_lshlrev_b64 v[66:67], 12, v[66:67]
	v_lshl_add_u64 v[66:67], s[88:89], 0, v[66:67]
	v_lshl_add_u64 v[66:67], v[66:67], 0, v[144:145]
	v_mul_f32_e32 v52, v52, v70
	v_mul_f32_e32 v53, v53, v70
	v_mul_f32_e32 v54, v54, v70
	v_mul_f32_e32 v55, v55, v70
	v_mul_f32_e32 v52, 0xbfb8aa3b, v52
	v_mul_f32_e32 v53, 0xbfb8aa3b, v53
	v_mul_f32_e32 v54, 0xbfb8aa3b, v54
	v_mul_f32_e32 v50, v50, v70
	v_mul_f32_e32 v55, 0xbfb8aa3b, v55
	v_mul_f32_e32 v51, v51, v70
	v_exp_f32_e32 v52, v52
	v_mul_f32_e32 v48, v48, v70
	v_exp_f32_e32 v53, v53
	v_mul_f32_e32 v49, v49, v70
	v_exp_f32_e32 v54, v54
	v_mul_f32_e32 v50, 0xbfb8aa3b, v50
	v_exp_f32_e32 v55, v55
	v_mul_f32_e32 v51, 0xbfb8aa3b, v51
	v_mul_f32_e32 v48, 0xbfb8aa3b, v48
	v_mul_f32_e32 v49, 0xbfb8aa3b, v49
	v_exp_f32_e32 v50, v50
	v_exp_f32_e32 v51, v51
	v_exp_f32_e32 v48, v48
	v_exp_f32_e32 v49, v49
	v_add_f32_e32 v52, 1.0, v52
	v_add_f32_e32 v53, 1.0, v53
	v_add_f32_e32 v54, 1.0, v54
	v_add_f32_e32 v55, 1.0, v55
	v_rcp_f32_e32 v52, v52
	v_rcp_f32_e32 v53, v53
	v_rcp_f32_e32 v54, v54
	v_add_f32_e32 v50, 1.0, v50
	v_rcp_f32_e32 v55, v55
	v_add_f32_e32 v51, 1.0, v51
	v_add_f32_e32 v48, 1.0, v48
	s_waitcnt vmcnt(1)
	v_lshlrev_b32_e32 v82, 16, v72
	v_and_b32_e32 v83, 0xffff0000, v72
	s_waitcnt vmcnt(0)
	v_lshlrev_b32_e32 v84, 16, v76
	v_and_b32_e32 v85, 0xffff0000, v76
	v_lshlrev_b32_e32 v72, 16, v73
	v_and_b32_e32 v73, 0xffff0000, v73
	v_lshlrev_b32_e32 v76, 16, v77
	v_and_b32_e32 v77, 0xffff0000, v77
	v_pk_fma_f32 v[60:61], v[60:61], v[84:85], v[82:83]
	v_lshlrev_b32_e32 v82, 16, v74
	v_and_b32_e32 v83, 0xffff0000, v74
	v_lshlrev_b32_e32 v84, 16, v78
	v_and_b32_e32 v85, 0xffff0000, v78
	v_pk_fma_f32 v[62:63], v[62:63], v[76:77], v[72:73]
	v_lshlrev_b32_e32 v72, 16, v75
	v_and_b32_e32 v73, 0xffff0000, v75
	v_lshlrev_b32_e32 v74, 16, v79
	v_and_b32_e32 v75, 0xffff0000, v79
	v_pk_fma_f32 v[56:57], v[56:57], v[84:85], v[82:83]
	v_pk_fma_f32 v[58:59], v[58:59], v[74:75], v[72:73]
	global_store_dwordx4 v[66:67], v[60:63], off nt
	global_store_dwordx4 v[66:67], v[56:59], off offset:16 nt
	global_load_dwordx4 v[56:59], v[64:65], off offset:256
	s_nop 0
	global_load_dwordx4 v[60:63], v[68:69], off offset:256
	v_add_f32_e32 v49, 1.0, v49
	v_rcp_f32_e32 v50, v50
	v_rcp_f32_e32 v51, v51
	v_rcp_f32_e32 v48, v48
	v_rcp_f32_e32 v49, v49
	s_waitcnt vmcnt(1)
	v_lshlrev_b32_e32 v64, 16, v56
	v_and_b32_e32 v65, 0xffff0000, v56
	s_waitcnt vmcnt(0)
	v_lshlrev_b32_e32 v68, 16, v60
	v_and_b32_e32 v69, 0xffff0000, v60
	v_lshlrev_b32_e32 v56, 16, v57
	v_and_b32_e32 v57, 0xffff0000, v57
	v_lshlrev_b32_e32 v60, 16, v61
	v_and_b32_e32 v61, 0xffff0000, v61
	v_pk_fma_f32 v[52:53], v[52:53], v[68:69], v[64:65]
	v_lshlrev_b32_e32 v64, 16, v58
	v_and_b32_e32 v65, 0xffff0000, v58
	v_pk_fma_f32 v[54:55], v[54:55], v[60:61], v[56:57]
	v_lshlrev_b32_e32 v56, 16, v59
	v_and_b32_e32 v57, 0xffff0000, v59
	v_lshlrev_b32_e32 v58, 16, v63
	v_and_b32_e32 v59, 0xffff0000, v63
	v_lshlrev_b32_e32 v68, 16, v62
	v_and_b32_e32 v69, 0xffff0000, v62
	v_pk_fma_f32 v[50:51], v[50:51], v[58:59], v[56:57]
	v_pk_fma_f32 v[48:49], v[48:49], v[68:69], v[64:65]
	global_store_dwordx4 v[66:67], v[52:55], off offset:512 nt
	global_store_dwordx4 v[66:67], v[48:51], off offset:528 nt
	s_nop 1
	v_add_u32_e32 v50, 0x90, v146
	v_ashrrev_i32_e32 v51, 31, v50
	v_lshl_add_u64 v[48:49], v[50:51], 2, s[90:91]
	v_add_co_u32_e32 v48, vcc, s11, v48
	s_nop 1
	v_addc_co_u32_e32 v49, vcc, 0, v49, vcc
	s_nop 0
	s_waitcnt vmcnt(42)
	v_fmamk_f32 v48, v247, 0x3a800000, v194
	v_cmp_gt_f32_e32 vcc, s19, v48
	v_mul_f32_e32 v49, 0x4b800000, v48
	s_nop 0
	v_cndmask_b32_e32 v48, v48, v49, vcc
	v_rsq_f32_e32 v48, v48
	s_nop 0
	v_mul_f32_e32 v49, 0x45800000, v48
	v_cndmask_b32_e32 v54, v48, v49, vcc
	v_lshlrev_b64 v[48:49], 11, v[50:51]
	v_lshl_add_u64 v[56:57], s[38:39], 0, v[48:49]
	v_lshl_add_u64 v[52:53], s[92:93], 0, v[48:49]
	v_lshl_add_u64 v[48:49], v[56:57], 0, v[142:143]
	v_lshl_add_u64 v[52:53], v[52:53], 0, v[142:143]
	global_load_dwordx4 v[56:59], v[48:49], off
	global_load_dwordx4 v[60:63], v[52:53], off
	v_mul_f32_e32 v44, v44, v54
	v_mul_f32_e32 v45, v45, v54
	v_mul_f32_e32 v46, v46, v54
	v_mul_f32_e32 v47, v47, v54
	v_mul_f32_e32 v44, 0xbfb8aa3b, v44
	v_mul_f32_e32 v40, v40, v54
	v_mul_f32_e32 v45, 0xbfb8aa3b, v45
	v_mul_f32_e32 v41, v41, v54
	v_mul_f32_e32 v46, 0xbfb8aa3b, v46
	v_mul_f32_e32 v42, v42, v54
	v_mul_f32_e32 v47, 0xbfb8aa3b, v47
	v_mul_f32_e32 v43, v43, v54
	v_exp_f32_e32 v44, v44
	v_mul_f32_e32 v40, 0xbfb8aa3b, v40
	v_exp_f32_e32 v45, v45
	v_mul_f32_e32 v41, 0xbfb8aa3b, v41
	v_exp_f32_e32 v46, v46
	v_mul_f32_e32 v42, 0xbfb8aa3b, v42
	v_exp_f32_e32 v47, v47
	v_mul_f32_e32 v43, 0xbfb8aa3b, v43
	v_exp_f32_e32 v40, v40
	v_exp_f32_e32 v41, v41
	v_exp_f32_e32 v42, v42
	v_exp_f32_e32 v43, v43
	v_add_f32_e32 v44, 1.0, v44
	v_add_f32_e32 v45, 1.0, v45
	v_add_f32_e32 v46, 1.0, v46
	v_add_f32_e32 v47, 1.0, v47
	v_rcp_f32_e32 v44, v44
	v_add_f32_e32 v40, 1.0, v40
	v_rcp_f32_e32 v45, v45
	v_add_f32_e32 v41, 1.0, v41
	v_rcp_f32_e32 v46, v46
	v_add_f32_e32 v42, 1.0, v42
	v_rcp_f32_e32 v47, v47
	v_add_f32_e32 v43, 1.0, v43
	v_rcp_f32_e32 v40, v40
	v_rcp_f32_e32 v41, v41
	v_rcp_f32_e32 v42, v42
	v_rcp_f32_e32 v43, v43
	v_lshlrev_b64 v[50:51], 12, v[50:51]
	v_lshl_add_u64 v[50:51], s[88:89], 0, v[50:51]
	v_lshl_add_u64 v[50:51], v[50:51], 0, v[144:145]
	v_mul_f32_e32 v36, v36, v54
	v_mul_f32_e32 v37, v37, v54
	v_mul_f32_e32 v38, v38, v54
	v_mul_f32_e32 v39, v39, v54
	v_mul_f32_e32 v36, 0xbfb8aa3b, v36
	v_mul_f32_e32 v37, 0xbfb8aa3b, v37
	v_mul_f32_e32 v38, 0xbfb8aa3b, v38
	v_mul_f32_e32 v34, v34, v54
	v_mul_f32_e32 v39, 0xbfb8aa3b, v39
	v_mul_f32_e32 v35, v35, v54
	v_exp_f32_e32 v36, v36
	v_mul_f32_e32 v32, v32, v54
	v_exp_f32_e32 v37, v37
	v_mul_f32_e32 v33, v33, v54
	v_exp_f32_e32 v38, v38
	v_mul_f32_e32 v34, 0xbfb8aa3b, v34
	v_exp_f32_e32 v39, v39
	v_mul_f32_e32 v35, 0xbfb8aa3b, v35
	v_mul_f32_e32 v32, 0xbfb8aa3b, v32
	v_mul_f32_e32 v33, 0xbfb8aa3b, v33
	v_exp_f32_e32 v34, v34
	v_exp_f32_e32 v35, v35
	v_exp_f32_e32 v32, v32
	v_exp_f32_e32 v33, v33
	v_add_f32_e32 v36, 1.0, v36
	v_add_f32_e32 v37, 1.0, v37
	v_add_f32_e32 v38, 1.0, v38
	v_add_f32_e32 v39, 1.0, v39
	v_rcp_f32_e32 v36, v36
	v_rcp_f32_e32 v37, v37
	v_rcp_f32_e32 v38, v38
	v_add_f32_e32 v34, 1.0, v34
	v_rcp_f32_e32 v39, v39
	v_add_f32_e32 v35, 1.0, v35
	v_add_f32_e32 v32, 1.0, v32
	s_waitcnt vmcnt(1)
	v_lshlrev_b32_e32 v64, 16, v56
	v_and_b32_e32 v65, 0xffff0000, v56
	s_waitcnt vmcnt(0)
	v_lshlrev_b32_e32 v66, 16, v60
	v_and_b32_e32 v67, 0xffff0000, v60
	v_lshlrev_b32_e32 v56, 16, v57
	v_and_b32_e32 v57, 0xffff0000, v57
	v_lshlrev_b32_e32 v60, 16, v61
	v_and_b32_e32 v61, 0xffff0000, v61
	v_pk_fma_f32 v[44:45], v[44:45], v[66:67], v[64:65]
	v_lshlrev_b32_e32 v64, 16, v58
	v_and_b32_e32 v65, 0xffff0000, v58
	v_lshlrev_b32_e32 v66, 16, v62
	v_and_b32_e32 v67, 0xffff0000, v62
	v_pk_fma_f32 v[46:47], v[46:47], v[60:61], v[56:57]
	v_lshlrev_b32_e32 v56, 16, v59
	v_and_b32_e32 v57, 0xffff0000, v59
	v_lshlrev_b32_e32 v58, 16, v63
	v_and_b32_e32 v59, 0xffff0000, v63
	v_pk_fma_f32 v[40:41], v[40:41], v[66:67], v[64:65]
	v_pk_fma_f32 v[42:43], v[42:43], v[58:59], v[56:57]
	global_store_dwordx4 v[50:51], v[44:47], off nt
	global_store_dwordx4 v[50:51], v[40:43], off offset:16 nt
	global_load_dwordx4 v[40:43], v[48:49], off offset:256
	s_nop 0
	global_load_dwordx4 v[44:47], v[52:53], off offset:256
	v_add_f32_e32 v33, 1.0, v33
	v_rcp_f32_e32 v34, v34
	v_rcp_f32_e32 v35, v35
	v_rcp_f32_e32 v32, v32
	v_rcp_f32_e32 v33, v33
	s_waitcnt vmcnt(1)
	v_lshlrev_b32_e32 v48, 16, v40
	v_and_b32_e32 v49, 0xffff0000, v40
	s_waitcnt vmcnt(0)
	v_lshlrev_b32_e32 v52, 16, v44
	v_and_b32_e32 v53, 0xffff0000, v44
	v_lshlrev_b32_e32 v40, 16, v41
	v_and_b32_e32 v41, 0xffff0000, v41
	v_lshlrev_b32_e32 v44, 16, v45
	v_and_b32_e32 v45, 0xffff0000, v45
	v_pk_fma_f32 v[36:37], v[36:37], v[52:53], v[48:49]
	v_lshlrev_b32_e32 v48, 16, v42
	v_and_b32_e32 v49, 0xffff0000, v42
	v_pk_fma_f32 v[38:39], v[38:39], v[44:45], v[40:41]
	v_lshlrev_b32_e32 v40, 16, v43
	v_and_b32_e32 v41, 0xffff0000, v43
	v_lshlrev_b32_e32 v42, 16, v47
	v_and_b32_e32 v43, 0xffff0000, v47
	v_lshlrev_b32_e32 v52, 16, v46
	v_and_b32_e32 v53, 0xffff0000, v46
	v_pk_fma_f32 v[34:35], v[34:35], v[42:43], v[40:41]
	v_pk_fma_f32 v[32:33], v[32:33], v[52:53], v[48:49]
	global_store_dwordx4 v[50:51], v[36:39], off offset:512 nt
	global_store_dwordx4 v[50:51], v[32:35], off offset:528 nt
	s_nop 1
	v_add_u32_e32 v34, 0xa0, v146
	v_ashrrev_i32_e32 v35, 31, v34
	v_lshl_add_u64 v[32:33], v[34:35], 2, s[90:91]
	v_add_co_u32_e32 v32, vcc, s11, v32
	s_nop 1
	v_addc_co_u32_e32 v33, vcc, 0, v33, vcc
	s_nop 0
	s_waitcnt vmcnt(49)
	v_fmamk_f32 v32, v248, 0x3a800000, v194
	v_cmp_gt_f32_e32 vcc, s19, v32
	v_mul_f32_e32 v33, 0x4b800000, v32
	s_nop 0
	v_cndmask_b32_e32 v32, v32, v33, vcc
	v_rsq_f32_e32 v32, v32
	s_nop 0
	v_mul_f32_e32 v33, 0x45800000, v32
	v_cndmask_b32_e32 v38, v32, v33, vcc
	v_lshlrev_b64 v[32:33], 11, v[34:35]
	v_lshl_add_u64 v[40:41], s[38:39], 0, v[32:33]
	v_lshl_add_u64 v[36:37], s[92:93], 0, v[32:33]
	v_lshl_add_u64 v[32:33], v[40:41], 0, v[142:143]
	v_lshl_add_u64 v[36:37], v[36:37], 0, v[142:143]
	global_load_dwordx4 v[40:43], v[32:33], off
	global_load_dwordx4 v[44:47], v[36:37], off
	v_mul_f32_e32 v28, v28, v38
	v_mul_f32_e32 v29, v29, v38
	v_mul_f32_e32 v30, v30, v38
	v_mul_f32_e32 v31, v31, v38
	v_mul_f32_e32 v28, 0xbfb8aa3b, v28
	v_mul_f32_e32 v24, v24, v38
	v_mul_f32_e32 v29, 0xbfb8aa3b, v29
	v_mul_f32_e32 v25, v25, v38
	v_mul_f32_e32 v30, 0xbfb8aa3b, v30
	v_mul_f32_e32 v26, v26, v38
	v_mul_f32_e32 v31, 0xbfb8aa3b, v31
	v_mul_f32_e32 v27, v27, v38
	v_exp_f32_e32 v28, v28
	v_mul_f32_e32 v24, 0xbfb8aa3b, v24
	v_exp_f32_e32 v29, v29
	v_mul_f32_e32 v25, 0xbfb8aa3b, v25
	v_exp_f32_e32 v30, v30
	v_mul_f32_e32 v26, 0xbfb8aa3b, v26
	v_exp_f32_e32 v31, v31
	v_mul_f32_e32 v27, 0xbfb8aa3b, v27
	v_exp_f32_e32 v24, v24
	v_exp_f32_e32 v25, v25
	v_exp_f32_e32 v26, v26
	v_exp_f32_e32 v27, v27
	v_add_f32_e32 v28, 1.0, v28
	v_add_f32_e32 v29, 1.0, v29
	v_add_f32_e32 v30, 1.0, v30
	v_add_f32_e32 v31, 1.0, v31
	v_rcp_f32_e32 v28, v28
	v_add_f32_e32 v24, 1.0, v24
	v_rcp_f32_e32 v29, v29
	v_add_f32_e32 v25, 1.0, v25
	v_rcp_f32_e32 v30, v30
	v_add_f32_e32 v26, 1.0, v26
	v_rcp_f32_e32 v31, v31
	v_add_f32_e32 v27, 1.0, v27
	v_rcp_f32_e32 v24, v24
	v_rcp_f32_e32 v25, v25
	v_rcp_f32_e32 v26, v26
	v_rcp_f32_e32 v27, v27
	v_lshlrev_b64 v[34:35], 12, v[34:35]
	v_lshl_add_u64 v[34:35], s[88:89], 0, v[34:35]
	v_lshl_add_u64 v[34:35], v[34:35], 0, v[144:145]
	v_mul_f32_e32 v20, v20, v38
	v_mul_f32_e32 v21, v21, v38
	v_mul_f32_e32 v22, v22, v38
	v_mul_f32_e32 v23, v23, v38
	v_mul_f32_e32 v20, 0xbfb8aa3b, v20
	v_mul_f32_e32 v21, 0xbfb8aa3b, v21
	v_mul_f32_e32 v22, 0xbfb8aa3b, v22
	v_mul_f32_e32 v18, v18, v38
	v_mul_f32_e32 v23, 0xbfb8aa3b, v23
	v_mul_f32_e32 v19, v19, v38
	v_exp_f32_e32 v20, v20
	v_mul_f32_e32 v16, v16, v38
	v_exp_f32_e32 v21, v21
	v_mul_f32_e32 v17, v17, v38
	v_exp_f32_e32 v22, v22
	v_mul_f32_e32 v18, 0xbfb8aa3b, v18
	v_exp_f32_e32 v23, v23
	v_mul_f32_e32 v19, 0xbfb8aa3b, v19
	v_mul_f32_e32 v16, 0xbfb8aa3b, v16
	v_mul_f32_e32 v17, 0xbfb8aa3b, v17
	v_exp_f32_e32 v18, v18
	v_exp_f32_e32 v19, v19
	v_exp_f32_e32 v16, v16
	v_exp_f32_e32 v17, v17
	v_add_f32_e32 v20, 1.0, v20
	v_add_f32_e32 v21, 1.0, v21
	v_add_f32_e32 v22, 1.0, v22
	v_add_f32_e32 v23, 1.0, v23
	v_rcp_f32_e32 v20, v20
	v_rcp_f32_e32 v21, v21
	v_rcp_f32_e32 v22, v22
	v_add_f32_e32 v18, 1.0, v18
	v_rcp_f32_e32 v23, v23
	v_add_f32_e32 v19, 1.0, v19
	v_add_f32_e32 v16, 1.0, v16
	s_waitcnt vmcnt(1)
	v_lshlrev_b32_e32 v48, 16, v40
	v_and_b32_e32 v49, 0xffff0000, v40
	s_waitcnt vmcnt(0)
	v_lshlrev_b32_e32 v50, 16, v44
	v_and_b32_e32 v51, 0xffff0000, v44
	v_lshlrev_b32_e32 v40, 16, v41
	v_and_b32_e32 v41, 0xffff0000, v41
	v_lshlrev_b32_e32 v44, 16, v45
	v_and_b32_e32 v45, 0xffff0000, v45
	v_pk_fma_f32 v[28:29], v[28:29], v[50:51], v[48:49]
	v_lshlrev_b32_e32 v48, 16, v42
	v_and_b32_e32 v49, 0xffff0000, v42
	v_lshlrev_b32_e32 v50, 16, v46
	v_and_b32_e32 v51, 0xffff0000, v46
	v_pk_fma_f32 v[30:31], v[30:31], v[44:45], v[40:41]
	v_lshlrev_b32_e32 v40, 16, v43
	v_and_b32_e32 v41, 0xffff0000, v43
	v_lshlrev_b32_e32 v42, 16, v47
	v_and_b32_e32 v43, 0xffff0000, v47
	v_pk_fma_f32 v[24:25], v[24:25], v[50:51], v[48:49]
	v_pk_fma_f32 v[26:27], v[26:27], v[42:43], v[40:41]
	global_store_dwordx4 v[34:35], v[28:31], off nt
	global_store_dwordx4 v[34:35], v[24:27], off offset:16 nt
	global_load_dwordx4 v[24:27], v[32:33], off offset:256
	s_nop 0
	global_load_dwordx4 v[28:31], v[36:37], off offset:256
	v_add_f32_e32 v17, 1.0, v17
	v_rcp_f32_e32 v18, v18
	v_rcp_f32_e32 v19, v19
	v_rcp_f32_e32 v16, v16
	v_rcp_f32_e32 v17, v17
	s_waitcnt vmcnt(1)
	v_lshlrev_b32_e32 v32, 16, v24
	v_and_b32_e32 v33, 0xffff0000, v24
	s_waitcnt vmcnt(0)
	v_lshlrev_b32_e32 v36, 16, v28
	v_and_b32_e32 v37, 0xffff0000, v28
	v_lshlrev_b32_e32 v24, 16, v25
	v_and_b32_e32 v25, 0xffff0000, v25
	v_lshlrev_b32_e32 v28, 16, v29
	v_and_b32_e32 v29, 0xffff0000, v29
	v_pk_fma_f32 v[20:21], v[20:21], v[36:37], v[32:33]
	v_lshlrev_b32_e32 v32, 16, v26
	v_and_b32_e32 v33, 0xffff0000, v26
	v_pk_fma_f32 v[22:23], v[22:23], v[28:29], v[24:25]
	v_lshlrev_b32_e32 v24, 16, v27
	v_and_b32_e32 v25, 0xffff0000, v27
	v_lshlrev_b32_e32 v26, 16, v31
	v_and_b32_e32 v27, 0xffff0000, v31
	v_lshlrev_b32_e32 v36, 16, v30
	v_and_b32_e32 v37, 0xffff0000, v30
	v_pk_fma_f32 v[18:19], v[18:19], v[26:27], v[24:25]
	v_pk_fma_f32 v[16:17], v[16:17], v[36:37], v[32:33]
	global_store_dwordx4 v[34:35], v[20:23], off offset:512 nt
	global_store_dwordx4 v[34:35], v[16:19], off offset:528 nt
	s_nop 1
	v_add_u32_e32 v18, 0xb0, v146
	v_ashrrev_i32_e32 v19, 31, v18
	v_lshl_add_u64 v[16:17], v[18:19], 2, s[90:91]
	v_add_co_u32_e32 v16, vcc, s11, v16
	s_nop 1
	v_addc_co_u32_e32 v17, vcc, 0, v17, vcc
	s_nop 0
	s_waitcnt vmcnt(56)
	v_fmamk_f32 v16, v249, 0x3a800000, v194
	v_cmp_gt_f32_e32 vcc, s19, v16
	v_mul_f32_e32 v17, 0x4b800000, v16
	s_nop 0
	v_cndmask_b32_e32 v16, v16, v17, vcc
	v_rsq_f32_e32 v16, v16
	s_nop 0
	v_mul_f32_e32 v17, 0x45800000, v16
	v_cndmask_b32_e32 v22, v16, v17, vcc
	v_lshlrev_b64 v[16:17], 11, v[18:19]
	v_lshl_add_u64 v[24:25], s[38:39], 0, v[16:17]
	v_lshl_add_u64 v[20:21], s[92:93], 0, v[16:17]
	v_lshl_add_u64 v[16:17], v[24:25], 0, v[142:143]
	v_lshl_add_u64 v[20:21], v[20:21], 0, v[142:143]
	global_load_dwordx4 v[24:27], v[16:17], off
	global_load_dwordx4 v[28:31], v[20:21], off
	v_mul_f32_e32 v12, v12, v22
	v_mul_f32_e32 v13, v13, v22
	v_mul_f32_e32 v14, v14, v22
	v_mul_f32_e32 v15, v15, v22
	v_mul_f32_e32 v12, 0xbfb8aa3b, v12
	v_mul_f32_e32 v8, v8, v22
	v_mul_f32_e32 v13, 0xbfb8aa3b, v13
	v_mul_f32_e32 v9, v9, v22
	v_mul_f32_e32 v14, 0xbfb8aa3b, v14
	v_mul_f32_e32 v10, v10, v22
	v_mul_f32_e32 v15, 0xbfb8aa3b, v15
	v_mul_f32_e32 v11, v11, v22
	v_exp_f32_e32 v12, v12
	v_mul_f32_e32 v8, 0xbfb8aa3b, v8
	v_exp_f32_e32 v13, v13
	v_mul_f32_e32 v9, 0xbfb8aa3b, v9
	v_exp_f32_e32 v14, v14
	v_mul_f32_e32 v10, 0xbfb8aa3b, v10
	v_exp_f32_e32 v15, v15
	v_mul_f32_e32 v11, 0xbfb8aa3b, v11
	v_exp_f32_e32 v8, v8
	v_exp_f32_e32 v9, v9
	v_exp_f32_e32 v10, v10
	v_exp_f32_e32 v11, v11
	v_add_f32_e32 v12, 1.0, v12
	v_add_f32_e32 v13, 1.0, v13
	v_add_f32_e32 v14, 1.0, v14
	v_add_f32_e32 v15, 1.0, v15
	v_rcp_f32_e32 v12, v12
	v_add_f32_e32 v8, 1.0, v8
	v_rcp_f32_e32 v13, v13
	v_add_f32_e32 v9, 1.0, v9
	v_rcp_f32_e32 v14, v14
	v_add_f32_e32 v10, 1.0, v10
	v_rcp_f32_e32 v15, v15
	v_add_f32_e32 v11, 1.0, v11
	v_rcp_f32_e32 v8, v8
	v_rcp_f32_e32 v9, v9
	v_rcp_f32_e32 v10, v10
	v_rcp_f32_e32 v11, v11
	v_lshlrev_b64 v[18:19], 12, v[18:19]
	v_lshl_add_u64 v[18:19], s[88:89], 0, v[18:19]
	v_lshl_add_u64 v[18:19], v[18:19], 0, v[144:145]
	v_mul_f32_e32 v4, v4, v22
	v_mul_f32_e32 v5, v5, v22
	v_mul_f32_e32 v6, v6, v22
	v_mul_f32_e32 v7, v7, v22
	v_mul_f32_e32 v4, 0xbfb8aa3b, v4
	v_mul_f32_e32 v0, v0, v22
	v_mul_f32_e32 v5, 0xbfb8aa3b, v5
	v_mul_f32_e32 v1, v1, v22
	v_mul_f32_e32 v6, 0xbfb8aa3b, v6
	v_mul_f32_e32 v2, v2, v22
	v_mul_f32_e32 v7, 0xbfb8aa3b, v7
	v_mul_f32_e32 v3, v3, v22
	v_exp_f32_e32 v4, v4
	v_mul_f32_e32 v0, 0xbfb8aa3b, v0
	v_exp_f32_e32 v5, v5
	v_mul_f32_e32 v1, 0xbfb8aa3b, v1
	v_exp_f32_e32 v6, v6
	v_mul_f32_e32 v2, 0xbfb8aa3b, v2
	v_exp_f32_e32 v7, v7
	v_mul_f32_e32 v3, 0xbfb8aa3b, v3
	v_exp_f32_e32 v0, v0
	v_exp_f32_e32 v1, v1
	v_exp_f32_e32 v2, v2
	v_exp_f32_e32 v3, v3
	v_add_f32_e32 v4, 1.0, v4
	v_add_f32_e32 v5, 1.0, v5
	v_add_f32_e32 v6, 1.0, v6
	v_add_f32_e32 v7, 1.0, v7
	v_rcp_f32_e32 v4, v4
	v_add_f32_e32 v0, 1.0, v0
	v_rcp_f32_e32 v5, v5
	v_add_f32_e32 v1, 1.0, v1
	v_rcp_f32_e32 v6, v6
	v_add_f32_e32 v2, 1.0, v2
	v_rcp_f32_e32 v7, v7
	s_waitcnt vmcnt(1)
	v_lshlrev_b32_e32 v32, 16, v24
	v_and_b32_e32 v33, 0xffff0000, v24
	s_waitcnt vmcnt(0)
	v_lshlrev_b32_e32 v34, 16, v28
	v_and_b32_e32 v35, 0xffff0000, v28
	v_lshlrev_b32_e32 v24, 16, v25
	v_and_b32_e32 v25, 0xffff0000, v25
	v_lshlrev_b32_e32 v28, 16, v29
	v_and_b32_e32 v29, 0xffff0000, v29
	v_pk_fma_f32 v[12:13], v[12:13], v[34:35], v[32:33]
	v_lshlrev_b32_e32 v32, 16, v26
	v_and_b32_e32 v33, 0xffff0000, v26
	v_lshlrev_b32_e32 v34, 16, v30
	v_and_b32_e32 v35, 0xffff0000, v30
	v_pk_fma_f32 v[14:15], v[14:15], v[28:29], v[24:25]
	v_lshlrev_b32_e32 v24, 16, v27
	v_and_b32_e32 v25, 0xffff0000, v27
	v_lshlrev_b32_e32 v26, 16, v31
	v_and_b32_e32 v27, 0xffff0000, v31
	v_pk_fma_f32 v[8:9], v[8:9], v[34:35], v[32:33]
	v_pk_fma_f32 v[10:11], v[10:11], v[26:27], v[24:25]
	global_store_dwordx4 v[18:19], v[12:15], off nt
	global_store_dwordx4 v[18:19], v[8:11], off offset:16 nt
	global_load_dwordx4 v[8:11], v[16:17], off offset:256
	s_nop 0
	global_load_dwordx4 v[12:15], v[20:21], off offset:256
	v_add_f32_e32 v3, 1.0, v3
	v_rcp_f32_e32 v0, v0
	v_rcp_f32_e32 v1, v1
	v_rcp_f32_e32 v2, v2
	v_rcp_f32_e32 v3, v3
	s_andn2_b64 vcc, exec, s[42:43]
	s_waitcnt vmcnt(1)
	v_lshlrev_b32_e32 v16, 16, v8
	v_and_b32_e32 v17, 0xffff0000, v8
	s_waitcnt vmcnt(0)
	v_lshlrev_b32_e32 v20, 16, v12
	v_and_b32_e32 v21, 0xffff0000, v12
	v_lshlrev_b32_e32 v8, 16, v9
	v_and_b32_e32 v9, 0xffff0000, v9
	v_lshlrev_b32_e32 v12, 16, v13
	v_and_b32_e32 v13, 0xffff0000, v13
	v_pk_fma_f32 v[4:5], v[4:5], v[20:21], v[16:17]
	v_lshlrev_b32_e32 v16, 16, v10
	v_and_b32_e32 v17, 0xffff0000, v10
	v_lshlrev_b32_e32 v20, 16, v14
	v_and_b32_e32 v21, 0xffff0000, v14
	v_pk_fma_f32 v[6:7], v[6:7], v[12:13], v[8:9]
	v_lshlrev_b32_e32 v8, 16, v11
	v_and_b32_e32 v9, 0xffff0000, v11
	v_lshlrev_b32_e32 v10, 16, v15
	v_and_b32_e32 v11, 0xffff0000, v15
	v_pk_fma_f32 v[0:1], v[0:1], v[20:21], v[16:17]
	v_pk_fma_f32 v[2:3], v[2:3], v[10:11], v[8:9]
	global_store_dwordx4 v[18:19], v[4:7], off offset:512 nt
	global_store_dwordx4 v[18:19], v[0:3], off offset:528 nt
	s_cbranch_vccnz .LBB0_159
	s_andn2_b64 vcc, exec, s[0:1]
	s_cbranch_vccnz .LBB0_158
	s_barrier
	s_branch .LBB0_158
